# attention MODE 1 epilogue: per-row 16-lane sums by four DPP adds (quad_perm, row_half_mirror, row_mirror) instead of four serialized ds_bpermute round trips; plus the batched read-modify-write of the
# speedup vs baseline: 1.0018x; 1.0018x over previous
.LBB0_393:
	s_or_b64 exec, exec, s[0:1]
	s_waitcnt lgkmcnt(0)
	v_lshl_add_u32 v78, v226, 4, s2
	ds_read_b128 v[64:67], v78 offset:128
	ds_read_b128 v[68:71], v78 offset:160
	s_lshl_b64 s[0:1], s[96:97], 11
	s_add_u32 s0, s55, s0
	s_addc_u32 s1, s56, s1
	s_waitcnt lgkmcnt(1)
	v_rcp_f32_e32 v82, v64
	v_rcp_f32_e32 v83, v65
	v_rcp_f32_e32 v84, v66
	v_rcp_f32_e32 v77, v67
	ds_read_b128 v[64:67], v78 offset:192
	ds_read_b128 v[78:81], v78 offset:224
	s_lshl_b32 s2, s34, 13
	s_add_i32 s2, s2, 0
	s_waitcnt lgkmcnt(2)
	v_rcp_f32_e32 v73, v71
	s_waitcnt lgkmcnt(1)
	v_rcp_f32_e32 v71, v65
	s_add_i32 s2, s2, 0x12800
	v_lshlrev_b32_e32 v65, 1, v224
	v_add3_u32 v65, s2, v225, v65
	v_rcp_f32_e32 v76, v68
	s_waitcnt lgkmcnt(0)
	v_rcp_f32_e32 v68, v78
	v_rcp_f32_e32 v75, v69
	v_rcp_f32_e32 v74, v70
	v_rcp_f32_e32 v72, v64
	v_rcp_f32_e32 v70, v66
	v_rcp_f32_e32 v69, v67
	v_rcp_f32_e32 v67, v79
	v_rcp_f32_e32 v66, v80
	v_rcp_f32_e32 v64, v81
	v_lshlrev_b32_e32 v204, 4, v222
	s_lshl_b64 s[4:5], s[10:11], 11
	ds_read_u16 v128, v65
	ds_read_u16 v129, v65 offset:64
	ds_read_u16 v130, v65 offset:128
	ds_read_u16 v131, v65 offset:192
	ds_read_u16 v132, v65 offset:256
	ds_read_u16 v133, v65 offset:320
	ds_read_u16 v134, v65 offset:384
	ds_read_u16 v135, v65 offset:448
	ds_read_u16 v136, v65 offset:512
	ds_read_u16 v137, v65 offset:576
	ds_read_u16 v138, v65 offset:640
	ds_read_u16 v139, v65 offset:704
	ds_read_u16 v140, v65 offset:768
	ds_read_u16 v141, v65 offset:832
	ds_read_u16 v142, v65 offset:896
	ds_read_u16 v143, v65 offset:960
	ds_read_u16 v144, v65 offset:2048
	ds_read_u16 v145, v65 offset:2112
	ds_read_u16 v146, v65 offset:2176
	ds_read_u16 v147, v65 offset:2240
	ds_read_u16 v148, v65 offset:2304
	ds_read_u16 v149, v65 offset:2368
	ds_read_u16 v150, v65 offset:2432
	ds_read_u16 v151, v65 offset:2496
	ds_read_u16 v152, v65 offset:2560
	ds_read_u16 v153, v65 offset:2624
	ds_read_u16 v154, v65 offset:2688
	ds_read_u16 v155, v65 offset:2752
	ds_read_u16 v156, v65 offset:2816
	ds_read_u16 v157, v65 offset:2880
	ds_read_u16 v158, v65 offset:2944
	ds_read_u16 v159, v65 offset:3008
	ds_read_u16 v160, v65 offset:4096
	ds_read_u16 v161, v65 offset:4160
	ds_read_u16 v162, v65 offset:4224
	ds_read_u16 v163, v65 offset:4288
	ds_read_u16 v164, v65 offset:4352
	ds_read_u16 v165, v65 offset:4416
	ds_read_u16 v166, v65 offset:4480
	ds_read_u16 v167, v65 offset:4544
	ds_read_u16 v168, v65 offset:4608
	ds_read_u16 v169, v65 offset:4672
	ds_read_u16 v170, v65 offset:4736
	ds_read_u16 v171, v65 offset:4800
	ds_read_u16 v172, v65 offset:4864
	ds_read_u16 v173, v65 offset:4928
	ds_read_u16 v174, v65 offset:4992
	ds_read_u16 v175, v65 offset:5056
	ds_read_u16 v176, v65 offset:6144
	ds_read_u16 v177, v65 offset:6208
	ds_read_u16 v178, v65 offset:6272
	ds_read_u16 v179, v65 offset:6336
	ds_read_u16 v180, v65 offset:6400
	ds_read_u16 v181, v65 offset:6464
	ds_read_u16 v182, v65 offset:6528
	ds_read_u16 v183, v65 offset:6592
	ds_read_u16 v184, v65 offset:6656
	ds_read_u16 v185, v65 offset:6720
	ds_read_u16 v186, v65 offset:6784
	ds_read_u16 v187, v65 offset:6848
	ds_read_u16 v188, v65 offset:6912
	ds_read_u16 v189, v65 offset:6976
	ds_read_u16 v190, v65 offset:7040
	ds_read_u16 v191, v65 offset:7104
	v_mul_f32_e32 v48, v48, v82
	v_mul_f32_e32 v32, v32, v82
	v_mul_f32_e32 v16, v16, v82
	v_mul_f32_e32 v0, v0, v82
	v_mul_f32_e32 v49, v49, v83
	v_mul_f32_e32 v33, v33, v83
	v_mul_f32_e32 v17, v17, v83
	v_mul_f32_e32 v1, v1, v83
	v_mul_f32_e32 v50, v50, v84
	v_mul_f32_e32 v34, v34, v84
	v_mul_f32_e32 v18, v18, v84
	v_mul_f32_e32 v2, v2, v84
	v_mul_f32_e32 v51, v51, v77
	v_mul_f32_e32 v35, v35, v77
	v_mul_f32_e32 v19, v19, v77
	v_mul_f32_e32 v3, v3, v77
	v_mul_f32_e32 v52, v52, v76
	v_mul_f32_e32 v36, v36, v76
	v_mul_f32_e32 v20, v20, v76
	v_mul_f32_e32 v4, v4, v76
	v_mul_f32_e32 v53, v53, v75
	v_mul_f32_e32 v37, v37, v75
	v_mul_f32_e32 v21, v21, v75
	v_mul_f32_e32 v5, v5, v75
	v_mul_f32_e32 v54, v54, v74
	v_mul_f32_e32 v38, v38, v74
	v_mul_f32_e32 v22, v22, v74
	v_mul_f32_e32 v6, v6, v74
	v_mul_f32_e32 v55, v55, v73
	v_mul_f32_e32 v39, v39, v73
	v_mul_f32_e32 v23, v23, v73
	v_mul_f32_e32 v7, v7, v73
	v_mul_f32_e32 v56, v56, v72
	v_mul_f32_e32 v40, v40, v72
	v_mul_f32_e32 v24, v24, v72
	v_mul_f32_e32 v8, v8, v72
	v_mul_f32_e32 v57, v57, v71
	v_mul_f32_e32 v41, v41, v71
	v_mul_f32_e32 v25, v25, v71
	v_mul_f32_e32 v9, v9, v71
	v_mul_f32_e32 v58, v58, v70
	v_mul_f32_e32 v42, v42, v70
	v_mul_f32_e32 v26, v26, v70
	v_mul_f32_e32 v10, v10, v70
	v_mul_f32_e32 v59, v59, v69
	v_mul_f32_e32 v43, v43, v69
	v_mul_f32_e32 v27, v27, v69
	v_mul_f32_e32 v11, v11, v69
	v_mul_f32_e32 v60, v60, v68
	v_mul_f32_e32 v44, v44, v68
	v_mul_f32_e32 v28, v28, v68
	v_mul_f32_e32 v12, v12, v68
	v_mul_f32_e32 v61, v61, v67
	v_mul_f32_e32 v45, v45, v67
	v_mul_f32_e32 v29, v29, v67
	v_mul_f32_e32 v13, v13, v67
	v_mul_f32_e32 v62, v62, v66
	v_mul_f32_e32 v46, v46, v66
	v_mul_f32_e32 v30, v30, v66
	v_mul_f32_e32 v14, v14, v66
	v_mul_f32_e32 v63, v63, v64
	v_mul_f32_e32 v47, v47, v64
	v_mul_f32_e32 v31, v31, v64
	v_mul_f32_e32 v15, v15, v64
	s_waitcnt lgkmcnt(0)
	v_lshlrev_b32_e32 v128, 16, v128
	v_fma_f32 v48, -v217, v48, v128
	v_cvt_pk_bf16_f32 v48, v48, s0
	ds_write_b16 v65, v48
	v_lshlrev_b32_e32 v129, 16, v129
	v_fma_f32 v32, -v217, v32, v129
	v_cvt_pk_bf16_f32 v32, v32, s0
	ds_write_b16 v65, v32 offset:64
	v_lshlrev_b32_e32 v130, 16, v130
	v_fma_f32 v16, -v217, v16, v130
	v_cvt_pk_bf16_f32 v16, v16, s0
	ds_write_b16 v65, v16 offset:128
	v_lshlrev_b32_e32 v131, 16, v131
	v_fma_f32 v0, -v217, v0, v131
	v_cvt_pk_bf16_f32 v0, v0, s0
	ds_write_b16 v65, v0 offset:192
	v_lshlrev_b32_e32 v132, 16, v132
	v_fma_f32 v49, -v217, v49, v132
	v_cvt_pk_bf16_f32 v49, v49, s0
	ds_write_b16 v65, v49 offset:256
	v_lshlrev_b32_e32 v133, 16, v133
	v_fma_f32 v33, -v217, v33, v133
	v_cvt_pk_bf16_f32 v33, v33, s0
	ds_write_b16 v65, v33 offset:320
	v_lshlrev_b32_e32 v134, 16, v134
	v_fma_f32 v17, -v217, v17, v134
	v_cvt_pk_bf16_f32 v17, v17, s0
	ds_write_b16 v65, v17 offset:384
	v_lshlrev_b32_e32 v135, 16, v135
	v_fma_f32 v1, -v217, v1, v135
	v_cvt_pk_bf16_f32 v1, v1, s0
	ds_write_b16 v65, v1 offset:448
	v_lshlrev_b32_e32 v136, 16, v136
	v_fma_f32 v50, -v217, v50, v136
	v_cvt_pk_bf16_f32 v50, v50, s0
	ds_write_b16 v65, v50 offset:512
	v_lshlrev_b32_e32 v137, 16, v137
	v_fma_f32 v34, -v217, v34, v137
	v_cvt_pk_bf16_f32 v34, v34, s0
	ds_write_b16 v65, v34 offset:576
	v_lshlrev_b32_e32 v138, 16, v138
	v_fma_f32 v18, -v217, v18, v138
	v_cvt_pk_bf16_f32 v18, v18, s0
	ds_write_b16 v65, v18 offset:640
	v_lshlrev_b32_e32 v139, 16, v139
	v_fma_f32 v2, -v217, v2, v139
	v_cvt_pk_bf16_f32 v2, v2, s0
	ds_write_b16 v65, v2 offset:704
	v_lshlrev_b32_e32 v140, 16, v140
	v_fma_f32 v51, -v217, v51, v140
	v_cvt_pk_bf16_f32 v51, v51, s0
	ds_write_b16 v65, v51 offset:768
	v_lshlrev_b32_e32 v141, 16, v141
	v_fma_f32 v35, -v217, v35, v141
	v_cvt_pk_bf16_f32 v35, v35, s0
	ds_write_b16 v65, v35 offset:832
	v_lshlrev_b32_e32 v142, 16, v142
	v_fma_f32 v19, -v217, v19, v142
	v_cvt_pk_bf16_f32 v19, v19, s0
	ds_write_b16 v65, v19 offset:896
	v_lshlrev_b32_e32 v143, 16, v143
	v_fma_f32 v3, -v217, v3, v143
	v_cvt_pk_bf16_f32 v3, v3, s0
	ds_write_b16 v65, v3 offset:960
	v_lshlrev_b32_e32 v144, 16, v144
	v_fma_f32 v52, -v217, v52, v144
	v_cvt_pk_bf16_f32 v52, v52, s0
	ds_write_b16 v65, v52 offset:2048
	v_lshlrev_b32_e32 v145, 16, v145
	v_fma_f32 v36, -v217, v36, v145
	v_cvt_pk_bf16_f32 v36, v36, s0
	ds_write_b16 v65, v36 offset:2112
	v_lshlrev_b32_e32 v146, 16, v146
	v_fma_f32 v20, -v217, v20, v146
	v_cvt_pk_bf16_f32 v20, v20, s0
	ds_write_b16 v65, v20 offset:2176
	v_lshlrev_b32_e32 v147, 16, v147
	v_fma_f32 v4, -v217, v4, v147
	v_cvt_pk_bf16_f32 v4, v4, s0
	ds_write_b16 v65, v4 offset:2240
	v_lshlrev_b32_e32 v148, 16, v148
	v_fma_f32 v53, -v217, v53, v148
	v_cvt_pk_bf16_f32 v53, v53, s0
	ds_write_b16 v65, v53 offset:2304
	v_lshlrev_b32_e32 v149, 16, v149
	v_fma_f32 v37, -v217, v37, v149
	v_cvt_pk_bf16_f32 v37, v37, s0
	ds_write_b16 v65, v37 offset:2368
	v_lshlrev_b32_e32 v150, 16, v150
	v_fma_f32 v21, -v217, v21, v150
	v_cvt_pk_bf16_f32 v21, v21, s0
	ds_write_b16 v65, v21 offset:2432
	v_lshlrev_b32_e32 v151, 16, v151
	v_fma_f32 v5, -v217, v5, v151
	v_cvt_pk_bf16_f32 v5, v5, s0
	ds_write_b16 v65, v5 offset:2496
	v_lshlrev_b32_e32 v152, 16, v152
	v_fma_f32 v54, -v217, v54, v152
	v_cvt_pk_bf16_f32 v54, v54, s0
	ds_write_b16 v65, v54 offset:2560
	v_lshlrev_b32_e32 v153, 16, v153
	v_fma_f32 v38, -v217, v38, v153
	v_cvt_pk_bf16_f32 v38, v38, s0
	ds_write_b16 v65, v38 offset:2624
	v_lshlrev_b32_e32 v154, 16, v154
	v_fma_f32 v22, -v217, v22, v154
	v_cvt_pk_bf16_f32 v22, v22, s0
	ds_write_b16 v65, v22 offset:2688
	v_lshlrev_b32_e32 v155, 16, v155
	v_fma_f32 v6, -v217, v6, v155
	v_cvt_pk_bf16_f32 v6, v6, s0
	ds_write_b16 v65, v6 offset:2752
	v_lshlrev_b32_e32 v156, 16, v156
	v_fma_f32 v55, -v217, v55, v156
	v_cvt_pk_bf16_f32 v55, v55, s0
	ds_write_b16 v65, v55 offset:2816
	v_lshlrev_b32_e32 v157, 16, v157
	v_fma_f32 v39, -v217, v39, v157
	v_cvt_pk_bf16_f32 v39, v39, s0
	ds_write_b16 v65, v39 offset:2880
	v_lshlrev_b32_e32 v158, 16, v158
	v_fma_f32 v23, -v217, v23, v158
	v_cvt_pk_bf16_f32 v23, v23, s0
	ds_write_b16 v65, v23 offset:2944
	v_lshlrev_b32_e32 v159, 16, v159
	v_fma_f32 v7, -v217, v7, v159
	v_cvt_pk_bf16_f32 v7, v7, s0
	ds_write_b16 v65, v7 offset:3008
	v_lshlrev_b32_e32 v160, 16, v160
	v_fma_f32 v56, -v217, v56, v160
	v_cvt_pk_bf16_f32 v56, v56, s0
	ds_write_b16 v65, v56 offset:4096
	v_lshlrev_b32_e32 v161, 16, v161
	v_fma_f32 v40, -v217, v40, v161
	v_cvt_pk_bf16_f32 v40, v40, s0
	ds_write_b16 v65, v40 offset:4160
	v_lshlrev_b32_e32 v162, 16, v162
	v_fma_f32 v24, -v217, v24, v162
	v_cvt_pk_bf16_f32 v24, v24, s0
	ds_write_b16 v65, v24 offset:4224
	v_lshlrev_b32_e32 v163, 16, v163
	v_fma_f32 v8, -v217, v8, v163
	v_cvt_pk_bf16_f32 v8, v8, s0
	ds_write_b16 v65, v8 offset:4288
	v_lshlrev_b32_e32 v164, 16, v164
	v_fma_f32 v57, -v217, v57, v164
	v_cvt_pk_bf16_f32 v57, v57, s0
	ds_write_b16 v65, v57 offset:4352
	v_lshlrev_b32_e32 v165, 16, v165
	v_fma_f32 v41, -v217, v41, v165
	v_cvt_pk_bf16_f32 v41, v41, s0
	ds_write_b16 v65, v41 offset:4416
	v_lshlrev_b32_e32 v166, 16, v166
	v_fma_f32 v25, -v217, v25, v166
	v_cvt_pk_bf16_f32 v25, v25, s0
	ds_write_b16 v65, v25 offset:4480
	v_lshlrev_b32_e32 v167, 16, v167
	v_fma_f32 v9, -v217, v9, v167
	v_cvt_pk_bf16_f32 v9, v9, s0
	ds_write_b16 v65, v9 offset:4544
	v_lshlrev_b32_e32 v168, 16, v168
	v_fma_f32 v58, -v217, v58, v168
	v_cvt_pk_bf16_f32 v58, v58, s0
	ds_write_b16 v65, v58 offset:4608
	v_lshlrev_b32_e32 v169, 16, v169
	v_fma_f32 v42, -v217, v42, v169
	v_cvt_pk_bf16_f32 v42, v42, s0
	ds_write_b16 v65, v42 offset:4672
	v_lshlrev_b32_e32 v170, 16, v170
	v_fma_f32 v26, -v217, v26, v170
	v_cvt_pk_bf16_f32 v26, v26, s0
	ds_write_b16 v65, v26 offset:4736
	v_lshlrev_b32_e32 v171, 16, v171
	v_fma_f32 v10, -v217, v10, v171
	v_cvt_pk_bf16_f32 v10, v10, s0
	ds_write_b16 v65, v10 offset:4800
	v_lshlrev_b32_e32 v172, 16, v172
	v_fma_f32 v59, -v217, v59, v172
	v_cvt_pk_bf16_f32 v59, v59, s0
	ds_write_b16 v65, v59 offset:4864
	v_lshlrev_b32_e32 v173, 16, v173
	v_fma_f32 v43, -v217, v43, v173
	v_cvt_pk_bf16_f32 v43, v43, s0
	ds_write_b16 v65, v43 offset:4928
	v_lshlrev_b32_e32 v174, 16, v174
	v_fma_f32 v27, -v217, v27, v174
	v_cvt_pk_bf16_f32 v27, v27, s0
	ds_write_b16 v65, v27 offset:4992
	v_lshlrev_b32_e32 v175, 16, v175
	v_fma_f32 v11, -v217, v11, v175
	v_cvt_pk_bf16_f32 v11, v11, s0
	ds_write_b16 v65, v11 offset:5056
	v_lshlrev_b32_e32 v176, 16, v176
	v_fma_f32 v60, -v217, v60, v176
	v_cvt_pk_bf16_f32 v60, v60, s0
	ds_write_b16 v65, v60 offset:6144
	v_lshlrev_b32_e32 v177, 16, v177
	v_fma_f32 v44, -v217, v44, v177
	v_cvt_pk_bf16_f32 v44, v44, s0
	ds_write_b16 v65, v44 offset:6208
	v_lshlrev_b32_e32 v178, 16, v178
	v_fma_f32 v28, -v217, v28, v178
	v_cvt_pk_bf16_f32 v28, v28, s0
	ds_write_b16 v65, v28 offset:6272
	v_lshlrev_b32_e32 v179, 16, v179
	v_fma_f32 v12, -v217, v12, v179
	v_cvt_pk_bf16_f32 v12, v12, s0
	ds_write_b16 v65, v12 offset:6336
	v_lshlrev_b32_e32 v180, 16, v180
	v_fma_f32 v61, -v217, v61, v180
	v_cvt_pk_bf16_f32 v61, v61, s0
	ds_write_b16 v65, v61 offset:6400
	v_lshlrev_b32_e32 v181, 16, v181
	v_fma_f32 v45, -v217, v45, v181
	v_cvt_pk_bf16_f32 v45, v45, s0
	ds_write_b16 v65, v45 offset:6464
	v_lshlrev_b32_e32 v182, 16, v182
	v_fma_f32 v29, -v217, v29, v182
	v_cvt_pk_bf16_f32 v29, v29, s0
	ds_write_b16 v65, v29 offset:6528
	v_lshlrev_b32_e32 v183, 16, v183
	v_fma_f32 v13, -v217, v13, v183
	v_cvt_pk_bf16_f32 v13, v13, s0
	ds_write_b16 v65, v13 offset:6592
	v_lshlrev_b32_e32 v184, 16, v184
	v_fma_f32 v62, -v217, v62, v184
	v_cvt_pk_bf16_f32 v62, v62, s0
	ds_write_b16 v65, v62 offset:6656
	v_lshlrev_b32_e32 v185, 16, v185
	v_fma_f32 v46, -v217, v46, v185
	v_cvt_pk_bf16_f32 v46, v46, s0
	ds_write_b16 v65, v46 offset:6720
	v_lshlrev_b32_e32 v186, 16, v186
	v_fma_f32 v30, -v217, v30, v186
	v_cvt_pk_bf16_f32 v30, v30, s0
	ds_write_b16 v65, v30 offset:6784
	v_lshlrev_b32_e32 v187, 16, v187
	v_fma_f32 v14, -v217, v14, v187
	v_cvt_pk_bf16_f32 v14, v14, s0
	ds_write_b16 v65, v14 offset:6848
	v_lshlrev_b32_e32 v188, 16, v188
	v_fma_f32 v63, -v217, v63, v188
	v_cvt_pk_bf16_f32 v63, v63, s0
	ds_write_b16 v65, v63 offset:6912
	v_lshlrev_b32_e32 v189, 16, v189
	v_fma_f32 v47, -v217, v47, v189
	v_cvt_pk_bf16_f32 v47, v47, s0
	ds_write_b16 v65, v47 offset:6976
	v_lshlrev_b32_e32 v190, 16, v190
	v_fma_f32 v31, -v217, v31, v190
	v_cvt_pk_bf16_f32 v31, v31, s0
	ds_write_b16 v65, v31 offset:7040
	v_lshlrev_b32_e32 v191, 16, v191
	v_fma_f32 v15, -v217, v15, v191
	v_cvt_pk_bf16_f32 v15, v15, s0
	ds_write_b16 v65, v15 offset:7104
	v_lshlrev_b32_e32 v4, 5, v222
	v_add_u32_e32 v10, s2, v204
	v_lshl_add_u32 v11, v221, 8, v10
	s_waitcnt lgkmcnt(0)
	global_load_dwordx4 v[0:3], v4, s[20:21] offset:16
	s_nop 0
	global_load_dwordx4 v[4:7], v4, s[20:21]
	ds_read_b128 v[12:15], v11
	s_add_u32 s0, s0, s4
	s_addc_u32 s1, s1, s5
	v_lshl_add_u64 v[8:9], s[0:1], 0, v[204:205]
	v_lshlrev_b32_e32 v204, 11, v221
	s_waitcnt lgkmcnt(0)
	v_and_b32_e32 v17, 0xffff0000, v15
	v_and_b32_e32 v19, 0xffff0000, v14
	v_lshlrev_b32_e32 v16, 16, v15
	v_lshlrev_b32_e32 v18, 16, v14
	v_mov_b32_e32 v20, v17
	v_mov_b32_e32 v21, v19
	v_mov_b32_e32 v14, v16
	v_mov_b32_e32 v15, v18
	v_pk_mul_f32 v[20:21], v[20:21], v[20:21]
	v_and_b32_e32 v23, 0xffff0000, v12
	v_pk_fma_f32 v[14:15], v[14:15], v[14:15], v[20:21]
	v_and_b32_e32 v21, 0xffff0000, v13
	v_lshlrev_b32_e32 v20, 16, v13
	v_lshlrev_b32_e32 v22, 16, v12
	v_mov_b32_e32 v24, v23
	v_mov_b32_e32 v25, v21
	v_mov_b32_e32 v12, v22
	v_mov_b32_e32 v13, v20
	v_pk_mul_f32 v[24:25], v[24:25], v[24:25]
	s_mov_b64 s[0:1], 0
	v_pk_fma_f32 v[12:13], v[12:13], v[12:13], v[24:25]
	s_and_b64 vcc, exec, s[94:95]
	v_add_f32_e32 v11, v12, v13
	v_add_f32_e32 v11, v15, v11
	v_add_f32_e32 v11, v14, v11
	s_nop 1
	v_add_f32_dpp v11, v11, v11 quad_perm:[1,0,3,2] row_mask:0xf bank_mask:0xf
	s_nop 1
	v_add_f32_dpp v11, v11, v11 quad_perm:[2,3,0,1] row_mask:0xf bank_mask:0xf
	s_nop 1
	v_add_f32_dpp v11, v11, v11 row_half_mirror row_mask:0xf bank_mask:0xf
	s_nop 1
	v_add_f32_dpp v11, v11, v11 row_mirror row_mask:0xf bank_mask:0xf
	v_fmamk_f32 v11, v11, 0x3c000000, v218
	v_rsq_f32_e32 v11, v11
	s_nop 0
	v_mul_f32_e32 v24, 0x3f4ccccd, v11
	v_pk_mul_f32 v[12:13], v[24:25], v[22:23] op_sel_hi:[0,1]
	v_pk_mul_f32 v[14:15], v[24:25], v[20:21] op_sel_hi:[0,1]
	v_pk_mul_f32 v[16:17], v[24:25], v[16:17] op_sel_hi:[0,1]
	v_or_b32_e32 v11, 4, v221
	s_waitcnt vmcnt(1)
	v_pk_mul_f32 v[16:17], v[2:3], v[16:17]
	s_waitcnt vmcnt(0)
	v_pk_mul_f32 v[12:13], v[4:5], v[12:13]
	v_pk_mul_f32 v[14:15], v[6:7], v[14:15]
	v_cvt_pk_bf16_f32 v12, v12, v13
	v_cvt_pk_bf16_f32 v13, v14, v15
	v_pk_mul_f32 v[14:15], v[24:25], v[18:19] op_sel_hi:[0,1]
	v_pk_mul_f32 v[14:15], v[0:1], v[14:15]
	s_nop 0
	v_cvt_pk_bf16_f32 v14, v14, v15
	v_cvt_pk_bf16_f32 v15, v16, v17
	v_lshl_add_u64 v[16:17], v[8:9], 0, v[204:205]
	global_store_dwordx4 v[16:17], v[12:15], off
	v_lshlrev_b32_e32 v204, 11, v11
	s_nop 0
	v_lshl_add_u32 v12, v11, 8, v10
	ds_read_b128 v[12:15], v12
	v_or_b32_e32 v11, 8, v221
	s_waitcnt lgkmcnt(0)
	v_and_b32_e32 v17, 0xffff0000, v15
	v_and_b32_e32 v19, 0xffff0000, v14
	v_lshlrev_b32_e32 v16, 16, v15
	v_lshlrev_b32_e32 v18, 16, v14
	v_mov_b32_e32 v20, v17
	v_mov_b32_e32 v21, v19
	v_mov_b32_e32 v14, v16
	v_mov_b32_e32 v15, v18
	v_pk_mul_f32 v[20:21], v[20:21], v[20:21]
	v_and_b32_e32 v23, 0xffff0000, v12
	v_pk_fma_f32 v[14:15], v[14:15], v[14:15], v[20:21]
	v_and_b32_e32 v21, 0xffff0000, v13
	v_lshlrev_b32_e32 v20, 16, v13
	v_lshlrev_b32_e32 v22, 16, v12
	v_mov_b32_e32 v24, v23
	v_mov_b32_e32 v25, v21
	v_mov_b32_e32 v12, v22
	v_mov_b32_e32 v13, v20
	v_pk_mul_f32 v[24:25], v[24:25], v[24:25]
	s_nop 0
	v_pk_fma_f32 v[12:13], v[12:13], v[12:13], v[24:25]
	s_nop 0
	v_add_f32_e32 v12, v12, v13
	v_add_f32_e32 v12, v15, v12
	v_add_f32_e32 v12, v14, v12
	s_nop 1
	v_add_f32_dpp v12, v12, v12 quad_perm:[1,0,3,2] row_mask:0xf bank_mask:0xf
	s_nop 1
	v_add_f32_dpp v12, v12, v12 quad_perm:[2,3,0,1] row_mask:0xf bank_mask:0xf
	s_nop 1
	v_add_f32_dpp v12, v12, v12 row_half_mirror row_mask:0xf bank_mask:0xf
	s_nop 1
	v_add_f32_dpp v12, v12, v12 row_mirror row_mask:0xf bank_mask:0xf
	v_fmamk_f32 v12, v12, 0x3c000000, v218
	v_rsq_f32_e32 v12, v12
	s_nop 0
	v_mul_f32_e32 v24, 0x3f4ccccd, v12
	v_pk_mul_f32 v[12:13], v[24:25], v[22:23] op_sel_hi:[0,1]
	v_pk_mul_f32 v[14:15], v[24:25], v[20:21] op_sel_hi:[0,1]
	v_pk_mul_f32 v[12:13], v[4:5], v[12:13]
	v_pk_mul_f32 v[14:15], v[6:7], v[14:15]
	v_cvt_pk_bf16_f32 v12, v12, v13
	v_cvt_pk_bf16_f32 v13, v14, v15
	v_pk_mul_f32 v[14:15], v[24:25], v[18:19] op_sel_hi:[0,1]
	v_pk_mul_f32 v[16:17], v[24:25], v[16:17] op_sel_hi:[0,1]
	v_pk_mul_f32 v[14:15], v[0:1], v[14:15]
	v_pk_mul_f32 v[16:17], v[2:3], v[16:17]
	v_cvt_pk_bf16_f32 v14, v14, v15
	v_cvt_pk_bf16_f32 v15, v16, v17
	v_lshl_add_u64 v[16:17], v[8:9], 0, v[204:205]
	global_store_dwordx4 v[16:17], v[12:15], off
	v_lshlrev_b32_e32 v204, 11, v11
	s_nop 0
	v_lshl_add_u32 v12, v11, 8, v10
	ds_read_b128 v[12:15], v12
	v_or_b32_e32 v11, 12, v221
	s_waitcnt lgkmcnt(0)
	v_and_b32_e32 v17, 0xffff0000, v15
	v_and_b32_e32 v19, 0xffff0000, v14
	v_lshlrev_b32_e32 v16, 16, v15
	v_lshlrev_b32_e32 v18, 16, v14
	v_mov_b32_e32 v20, v17
	v_mov_b32_e32 v21, v19
	v_mov_b32_e32 v14, v16
	v_mov_b32_e32 v15, v18
	v_pk_mul_f32 v[20:21], v[20:21], v[20:21]
	v_and_b32_e32 v23, 0xffff0000, v12
	v_pk_fma_f32 v[14:15], v[14:15], v[14:15], v[20:21]
	v_and_b32_e32 v21, 0xffff0000, v13
	v_lshlrev_b32_e32 v20, 16, v13
	v_lshlrev_b32_e32 v22, 16, v12
	v_mov_b32_e32 v24, v23
	v_mov_b32_e32 v25, v21
	v_mov_b32_e32 v12, v22
	v_mov_b32_e32 v13, v20
	v_pk_mul_f32 v[24:25], v[24:25], v[24:25]
	s_nop 0
	v_pk_fma_f32 v[12:13], v[12:13], v[12:13], v[24:25]
	s_nop 0
	v_add_f32_e32 v12, v12, v13
	v_add_f32_e32 v12, v15, v12
	v_add_f32_e32 v12, v14, v12
	s_nop 1
	v_add_f32_dpp v12, v12, v12 quad_perm:[1,0,3,2] row_mask:0xf bank_mask:0xf
	s_nop 1
	v_add_f32_dpp v12, v12, v12 quad_perm:[2,3,0,1] row_mask:0xf bank_mask:0xf
	s_nop 1
	v_add_f32_dpp v12, v12, v12 row_half_mirror row_mask:0xf bank_mask:0xf
	s_nop 1
	v_add_f32_dpp v12, v12, v12 row_mirror row_mask:0xf bank_mask:0xf
	v_fmamk_f32 v12, v12, 0x3c000000, v218
	v_rsq_f32_e32 v12, v12
	s_nop 0
	v_mul_f32_e32 v24, 0x3f4ccccd, v12
	v_pk_mul_f32 v[12:13], v[24:25], v[22:23] op_sel_hi:[0,1]
	v_pk_mul_f32 v[14:15], v[24:25], v[20:21] op_sel_hi:[0,1]
	v_pk_mul_f32 v[12:13], v[4:5], v[12:13]
	v_pk_mul_f32 v[14:15], v[6:7], v[14:15]
	v_cvt_pk_bf16_f32 v12, v12, v13
	v_cvt_pk_bf16_f32 v13, v14, v15
	v_pk_mul_f32 v[14:15], v[24:25], v[18:19] op_sel_hi:[0,1]
	v_pk_mul_f32 v[16:17], v[24:25], v[16:17] op_sel_hi:[0,1]
	v_pk_mul_f32 v[14:15], v[0:1], v[14:15]
	v_pk_mul_f32 v[16:17], v[2:3], v[16:17]
	v_cvt_pk_bf16_f32 v14, v14, v15
	v_cvt_pk_bf16_f32 v15, v16, v17
	v_lshl_add_u64 v[16:17], v[8:9], 0, v[204:205]
	global_store_dwordx4 v[16:17], v[12:15], off
	v_lshlrev_b32_e32 v204, 11, v11
	s_nop 0
	v_lshl_add_u32 v12, v11, 8, v10
	ds_read_b128 v[12:15], v12
	v_or_b32_e32 v11, 16, v221
	s_waitcnt lgkmcnt(0)
	v_and_b32_e32 v17, 0xffff0000, v15
	v_and_b32_e32 v19, 0xffff0000, v14
	v_lshlrev_b32_e32 v16, 16, v15
	v_lshlrev_b32_e32 v18, 16, v14
	v_mov_b32_e32 v20, v17
	v_mov_b32_e32 v21, v19
	v_mov_b32_e32 v14, v16
	v_mov_b32_e32 v15, v18
	v_pk_mul_f32 v[20:21], v[20:21], v[20:21]
	v_and_b32_e32 v23, 0xffff0000, v12
	v_pk_fma_f32 v[14:15], v[14:15], v[14:15], v[20:21]
	v_and_b32_e32 v21, 0xffff0000, v13
	v_lshlrev_b32_e32 v20, 16, v13
	v_lshlrev_b32_e32 v22, 16, v12
	v_mov_b32_e32 v24, v23
	v_mov_b32_e32 v25, v21
	v_mov_b32_e32 v12, v22
	v_mov_b32_e32 v13, v20
	v_pk_mul_f32 v[24:25], v[24:25], v[24:25]
	s_nop 0
	v_pk_fma_f32 v[12:13], v[12:13], v[12:13], v[24:25]
	s_nop 0
	v_add_f32_e32 v12, v12, v13
	v_add_f32_e32 v12, v15, v12
	v_add_f32_e32 v12, v14, v12
	s_nop 1
	v_add_f32_dpp v12, v12, v12 quad_perm:[1,0,3,2] row_mask:0xf bank_mask:0xf
	s_nop 1
	v_add_f32_dpp v12, v12, v12 quad_perm:[2,3,0,1] row_mask:0xf bank_mask:0xf
	s_nop 1
	v_add_f32_dpp v12, v12, v12 row_half_mirror row_mask:0xf bank_mask:0xf
	s_nop 1
	v_add_f32_dpp v12, v12, v12 row_mirror row_mask:0xf bank_mask:0xf
	v_fmamk_f32 v12, v12, 0x3c000000, v218
	v_rsq_f32_e32 v12, v12
	s_nop 0
	v_mul_f32_e32 v24, 0x3f4ccccd, v12
	v_pk_mul_f32 v[12:13], v[24:25], v[22:23] op_sel_hi:[0,1]
	v_pk_mul_f32 v[14:15], v[24:25], v[20:21] op_sel_hi:[0,1]
	v_pk_mul_f32 v[12:13], v[4:5], v[12:13]
	v_pk_mul_f32 v[14:15], v[6:7], v[14:15]
	v_cvt_pk_bf16_f32 v12, v12, v13
	v_cvt_pk_bf16_f32 v13, v14, v15
	v_pk_mul_f32 v[14:15], v[24:25], v[18:19] op_sel_hi:[0,1]
	v_pk_mul_f32 v[16:17], v[24:25], v[16:17] op_sel_hi:[0,1]
	v_pk_mul_f32 v[14:15], v[0:1], v[14:15]
	v_pk_mul_f32 v[16:17], v[2:3], v[16:17]
	v_cvt_pk_bf16_f32 v14, v14, v15
	v_cvt_pk_bf16_f32 v15, v16, v17
	v_lshl_add_u64 v[16:17], v[8:9], 0, v[204:205]
	global_store_dwordx4 v[16:17], v[12:15], off
	v_lshlrev_b32_e32 v204, 11, v11
	s_nop 0
	v_lshl_add_u32 v12, v11, 8, v10
	ds_read_b128 v[12:15], v12
	v_or_b32_e32 v11, 20, v221
	s_waitcnt lgkmcnt(0)
	v_and_b32_e32 v17, 0xffff0000, v15
	v_and_b32_e32 v19, 0xffff0000, v14
	v_lshlrev_b32_e32 v16, 16, v15
	v_lshlrev_b32_e32 v18, 16, v14
	v_mov_b32_e32 v20, v17
	v_mov_b32_e32 v21, v19
	v_mov_b32_e32 v14, v16
	v_mov_b32_e32 v15, v18
	v_pk_mul_f32 v[20:21], v[20:21], v[20:21]
	v_and_b32_e32 v23, 0xffff0000, v12
	v_pk_fma_f32 v[14:15], v[14:15], v[14:15], v[20:21]
	v_and_b32_e32 v21, 0xffff0000, v13
	v_lshlrev_b32_e32 v20, 16, v13
	v_lshlrev_b32_e32 v22, 16, v12
	v_mov_b32_e32 v24, v23
	v_mov_b32_e32 v25, v21
	v_mov_b32_e32 v12, v22
	v_mov_b32_e32 v13, v20
	v_pk_mul_f32 v[24:25], v[24:25], v[24:25]
	s_nop 0
	v_pk_fma_f32 v[12:13], v[12:13], v[12:13], v[24:25]
	s_nop 0
	v_add_f32_e32 v12, v12, v13
	v_add_f32_e32 v12, v15, v12
	v_add_f32_e32 v12, v14, v12
	s_nop 1
	v_add_f32_dpp v12, v12, v12 quad_perm:[1,0,3,2] row_mask:0xf bank_mask:0xf
	s_nop 1
	v_add_f32_dpp v12, v12, v12 quad_perm:[2,3,0,1] row_mask:0xf bank_mask:0xf
	s_nop 1
	v_add_f32_dpp v12, v12, v12 row_half_mirror row_mask:0xf bank_mask:0xf
	s_nop 1
	v_add_f32_dpp v12, v12, v12 row_mirror row_mask:0xf bank_mask:0xf
	v_fmamk_f32 v12, v12, 0x3c000000, v218
	v_rsq_f32_e32 v12, v12
	s_nop 0
	v_mul_f32_e32 v24, 0x3f4ccccd, v12
	v_pk_mul_f32 v[12:13], v[24:25], v[22:23] op_sel_hi:[0,1]
	v_pk_mul_f32 v[14:15], v[24:25], v[20:21] op_sel_hi:[0,1]
	v_pk_mul_f32 v[12:13], v[4:5], v[12:13]
	v_pk_mul_f32 v[14:15], v[6:7], v[14:15]
	v_cvt_pk_bf16_f32 v12, v12, v13
	v_cvt_pk_bf16_f32 v13, v14, v15
	v_pk_mul_f32 v[14:15], v[24:25], v[18:19] op_sel_hi:[0,1]
	v_pk_mul_f32 v[16:17], v[24:25], v[16:17] op_sel_hi:[0,1]
	v_pk_mul_f32 v[14:15], v[0:1], v[14:15]
	v_pk_mul_f32 v[16:17], v[2:3], v[16:17]
	v_cvt_pk_bf16_f32 v14, v14, v15
	v_cvt_pk_bf16_f32 v15, v16, v17
	v_lshl_add_u64 v[16:17], v[8:9], 0, v[204:205]
	global_store_dwordx4 v[16:17], v[12:15], off
	v_lshlrev_b32_e32 v204, 11, v11
	s_nop 0
	v_lshl_add_u32 v12, v11, 8, v10
	ds_read_b128 v[12:15], v12
	v_or_b32_e32 v11, 24, v221
	s_waitcnt lgkmcnt(0)
	v_and_b32_e32 v17, 0xffff0000, v15
	v_and_b32_e32 v19, 0xffff0000, v14
	v_lshlrev_b32_e32 v16, 16, v15
	v_lshlrev_b32_e32 v18, 16, v14
	v_mov_b32_e32 v20, v17
	v_mov_b32_e32 v21, v19
	v_mov_b32_e32 v14, v16
	v_mov_b32_e32 v15, v18
	v_pk_mul_f32 v[20:21], v[20:21], v[20:21]
	v_and_b32_e32 v23, 0xffff0000, v12
	v_pk_fma_f32 v[14:15], v[14:15], v[14:15], v[20:21]
	v_and_b32_e32 v21, 0xffff0000, v13
	v_lshlrev_b32_e32 v20, 16, v13
	v_lshlrev_b32_e32 v22, 16, v12
	v_mov_b32_e32 v24, v23
	v_mov_b32_e32 v25, v21
	v_mov_b32_e32 v12, v22
	v_mov_b32_e32 v13, v20
	v_pk_mul_f32 v[24:25], v[24:25], v[24:25]
	s_nop 0
	v_pk_fma_f32 v[12:13], v[12:13], v[12:13], v[24:25]
	s_nop 0
	v_add_f32_e32 v12, v12, v13
	v_add_f32_e32 v12, v15, v12
	v_add_f32_e32 v12, v14, v12
	s_nop 1
	v_add_f32_dpp v12, v12, v12 quad_perm:[1,0,3,2] row_mask:0xf bank_mask:0xf
	s_nop 1
	v_add_f32_dpp v12, v12, v12 quad_perm:[2,3,0,1] row_mask:0xf bank_mask:0xf
	s_nop 1
	v_add_f32_dpp v12, v12, v12 row_half_mirror row_mask:0xf bank_mask:0xf
	s_nop 1
	v_add_f32_dpp v12, v12, v12 row_mirror row_mask:0xf bank_mask:0xf
	v_fmamk_f32 v12, v12, 0x3c000000, v218
	v_rsq_f32_e32 v12, v12
	s_nop 0
	v_mul_f32_e32 v24, 0x3f4ccccd, v12
	v_pk_mul_f32 v[12:13], v[24:25], v[22:23] op_sel_hi:[0,1]
	v_pk_mul_f32 v[14:15], v[24:25], v[20:21] op_sel_hi:[0,1]
	v_pk_mul_f32 v[12:13], v[4:5], v[12:13]
	v_pk_mul_f32 v[14:15], v[6:7], v[14:15]
	v_cvt_pk_bf16_f32 v12, v12, v13
	v_cvt_pk_bf16_f32 v13, v14, v15
	v_pk_mul_f32 v[14:15], v[24:25], v[18:19] op_sel_hi:[0,1]
	v_pk_mul_f32 v[16:17], v[24:25], v[16:17] op_sel_hi:[0,1]
	v_pk_mul_f32 v[14:15], v[0:1], v[14:15]
	v_pk_mul_f32 v[16:17], v[2:3], v[16:17]
	v_cvt_pk_bf16_f32 v14, v14, v15
	v_cvt_pk_bf16_f32 v15, v16, v17
	v_lshl_add_u64 v[16:17], v[8:9], 0, v[204:205]
	global_store_dwordx4 v[16:17], v[12:15], off
	v_lshlrev_b32_e32 v204, 11, v11
	s_nop 0
	v_lshl_add_u32 v12, v11, 8, v10
	ds_read_b128 v[12:15], v12
	s_waitcnt lgkmcnt(0)
	v_and_b32_e32 v17, 0xffff0000, v15
	v_and_b32_e32 v19, 0xffff0000, v14
	v_lshlrev_b32_e32 v16, 16, v15
	v_lshlrev_b32_e32 v18, 16, v14
	v_mov_b32_e32 v20, v17
	v_mov_b32_e32 v21, v19
	v_mov_b32_e32 v14, v16
	v_mov_b32_e32 v15, v18
	v_pk_mul_f32 v[20:21], v[20:21], v[20:21]
	v_and_b32_e32 v23, 0xffff0000, v12
	v_pk_fma_f32 v[14:15], v[14:15], v[14:15], v[20:21]
	v_and_b32_e32 v21, 0xffff0000, v13
	v_lshlrev_b32_e32 v20, 16, v13
	v_lshlrev_b32_e32 v22, 16, v12
	v_mov_b32_e32 v24, v23
	v_mov_b32_e32 v25, v21
	v_mov_b32_e32 v12, v22
	v_mov_b32_e32 v13, v20
	v_pk_mul_f32 v[24:25], v[24:25], v[24:25]
	s_nop 0
	v_pk_fma_f32 v[12:13], v[12:13], v[12:13], v[24:25]
	s_nop 0
	v_add_f32_e32 v12, v12, v13
	v_add_f32_e32 v12, v15, v12
	v_add_f32_e32 v12, v14, v12
	s_nop 1
	v_add_f32_dpp v12, v12, v12 quad_perm:[1,0,3,2] row_mask:0xf bank_mask:0xf
	s_nop 1
	v_add_f32_dpp v12, v12, v12 quad_perm:[2,3,0,1] row_mask:0xf bank_mask:0xf
	s_nop 1
	v_add_f32_dpp v12, v12, v12 row_half_mirror row_mask:0xf bank_mask:0xf
	s_nop 1
	v_add_f32_dpp v12, v12, v12 row_mirror row_mask:0xf bank_mask:0xf
	v_fmamk_f32 v12, v12, 0x3c000000, v218
	v_rsq_f32_e32 v12, v12
	s_nop 0
	v_mul_f32_e32 v24, 0x3f4ccccd, v12
	v_pk_mul_f32 v[12:13], v[24:25], v[22:23] op_sel_hi:[0,1]
	v_pk_mul_f32 v[14:15], v[24:25], v[20:21] op_sel_hi:[0,1]
	v_pk_mul_f32 v[12:13], v[4:5], v[12:13]
	v_pk_mul_f32 v[14:15], v[6:7], v[14:15]
	v_cvt_pk_bf16_f32 v12, v12, v13
	v_cvt_pk_bf16_f32 v13, v14, v15
	v_pk_mul_f32 v[14:15], v[24:25], v[18:19] op_sel_hi:[0,1]
	v_pk_mul_f32 v[16:17], v[24:25], v[16:17] op_sel_hi:[0,1]
	v_pk_mul_f32 v[14:15], v[0:1], v[14:15]
	v_pk_mul_f32 v[16:17], v[2:3], v[16:17]
	v_or_b32_e32 v24, 28, v221
	v_cvt_pk_bf16_f32 v14, v14, v15
	v_cvt_pk_bf16_f32 v15, v16, v17
	v_lshl_add_u64 v[16:17], v[8:9], 0, v[204:205]
	v_lshl_add_u32 v10, v24, 8, v10
	global_store_dwordx4 v[16:17], v[12:15], off
	ds_read_b128 v[10:13], v10
	v_lshlrev_b32_e32 v204, 11, v24
	s_waitcnt lgkmcnt(0)
	v_and_b32_e32 v15, 0xffff0000, v13
	v_and_b32_e32 v17, 0xffff0000, v12
	v_lshlrev_b32_e32 v14, 16, v13
	v_lshlrev_b32_e32 v16, 16, v12
	v_mov_b32_e32 v18, v15
	v_mov_b32_e32 v19, v17
	v_mov_b32_e32 v12, v14
	v_mov_b32_e32 v13, v16
	v_pk_mul_f32 v[18:19], v[18:19], v[18:19]
	v_and_b32_e32 v21, 0xffff0000, v10
	v_pk_fma_f32 v[12:13], v[12:13], v[12:13], v[18:19]
	v_and_b32_e32 v19, 0xffff0000, v11
	v_lshlrev_b32_e32 v18, 16, v11
	v_lshlrev_b32_e32 v20, 16, v10
	v_mov_b32_e32 v22, v21
	v_mov_b32_e32 v23, v19
	v_mov_b32_e32 v10, v20
	v_mov_b32_e32 v11, v18
	v_pk_mul_f32 v[22:23], v[22:23], v[22:23]
	s_nop 0
	v_pk_fma_f32 v[10:11], v[10:11], v[10:11], v[22:23]
	s_nop 0
	v_add_f32_e32 v10, v10, v11
	v_add_f32_e32 v10, v13, v10
	v_add_f32_e32 v10, v12, v10
	s_nop 1
	v_add_f32_dpp v10, v10, v10 quad_perm:[1,0,3,2] row_mask:0xf bank_mask:0xf
	s_nop 1
	v_add_f32_dpp v10, v10, v10 quad_perm:[2,3,0,1] row_mask:0xf bank_mask:0xf
	s_nop 1
	v_add_f32_dpp v10, v10, v10 row_half_mirror row_mask:0xf bank_mask:0xf
	s_nop 1
	v_add_f32_dpp v10, v10, v10 row_mirror row_mask:0xf bank_mask:0xf
	v_fmamk_f32 v10, v10, 0x3c000000, v218
	v_rsq_f32_e32 v10, v10
	s_nop 0
	v_mul_f32_e32 v10, 0x3f4ccccd, v10
	v_pk_mul_f32 v[12:13], v[10:11], v[20:21] op_sel_hi:[0,1]
	v_pk_mul_f32 v[4:5], v[4:5], v[12:13]
	v_pk_mul_f32 v[12:13], v[10:11], v[18:19] op_sel_hi:[0,1]
	v_pk_mul_f32 v[6:7], v[6:7], v[12:13]
	v_cvt_pk_bf16_f32 v4, v4, v5
	v_cvt_pk_bf16_f32 v5, v6, v7
	v_pk_mul_f32 v[6:7], v[10:11], v[16:17] op_sel_hi:[0,1]
	v_pk_mul_f32 v[0:1], v[0:1], v[6:7]
	s_nop 0
	v_cvt_pk_bf16_f32 v6, v0, v1
	v_pk_mul_f32 v[0:1], v[10:11], v[14:15] op_sel_hi:[0,1]
	v_pk_mul_f32 v[0:1], v[2:3], v[0:1]
	s_nop 0
	v_cvt_pk_bf16_f32 v7, v0, v1
	v_lshl_add_u64 v[0:1], v[8:9], 0, v[204:205]
	global_store_dwordx4 v[0:1], v[4:7], off
	s_waitcnt lgkmcnt(0)
	s_waitcnt lgkmcnt(0)
	s_barrier
	s_cbranch_vccnz .LBB0_391
